# strategy 8: counted lgkmcnt(12) before the first four S=K.Q MFMAs of the window attention tile loop (MFMA starts while the remaining K fragments are still being read from LDS)
# speedup vs baseline: 1.0107x; 1.0107x over previous
; __device__ __forceinline__ void tile_dma(unsigned char* lds, int slot, const bf16_t* Kg, const bf16_t* Vtg, int kb, int tid) {
;     unsigned char* kd = lds + slot * RING_SLOT; unsigned char* vd = kd + RING_V;
; #pragma unroll
;     for (int i = 0; i < 2; ++i) {
;         const int q = i * 512 + tid;
;         { const int rs = q >> 4, pos = q & 15, c = pos ^ (rs & 15), nt = rs >> 4, r16 = rs & 15;
;           const int keyl = 32 * (nt >> 1) + 8 * (r16 >> 2) + 4 * (nt & 1) + (r16 & 3);
;           __builtin_amdgcn_global_load_lds((const unsigned*)(Kg + ((size_t)kb * 64 + keyl) * 128 + c * 8),
;                                            (__attribute__((address_space(3))) unsigned*)(kd + q * 16), 16, 0, 0); }
;         { const int d = q >> 3, pos = q & 7, c = pos ^ ((d >> 1) & 7);
;           __builtin_amdgcn_global_load_lds((const unsigned*)(Vtg + (size_t)d * SEQ + kb * 64 + c * 8),
;                                            (__attribute__((address_space(3))) unsigned*)(vd + q * 16), 16, 0, 0); }
;     }
; template <int MODE>
; __device__ __forceinline__ void attn_compute(const bf16x8 (&qf)[4], const unsigned char* Ks, const unsigned char* Vs, int kb, int tok,
;                                              unsigned long long msk, f32x4 (&O)[8], float& mrow, float& lrow) {
;     ...
;     if (MODE == 1) {
;         if (__builtin_amdgcn_ballot_w64(((msk >> kb) & 1ull) != 0ull) == 0ull) return;
;     }
;     f32x4 S[4];
;     {
;         bf16x8 kf[16];
; #pragma unroll
;         for (int i = 0; i < 16; ++i) kf[i] = *(const bf16x8*)(Ks + ((i >> 2) * 16 + fr) * 256 + ((((i & 3) * 4 + fq) ^ fr) * 16));
;         __builtin_amdgcn_sched_barrier(0);
; #pragma unroll
;         for (int nt = 0; nt < 4; ++nt) {
;             S[nt] = zero4();
; #pragma unroll
;             for (int ks = 0; ks < 4; ++ks) S[nt] = mfma16(kf[nt * 4 + ks], qf[ks], S[nt]);
;         }
;     }
;     bf16x8 vf[16];
; #pragma unroll
;     for (int i = 0; i < 16; ++i) vf[i] = *(const bf16x8*)(Vs + ((i & 7) * 16 + fr) * 128 + ((((i >> 3) * 4 + fq) ^ ((fr >> 1) & 7)) * 16));
;     const bool rowok = (MODE == 0) ? true : (((msk >> kb) & 1ull) != 0ull);
;     const int key0 = kb * 64 + 8 * fq;
;     const int tb = __builtin_amdgcn_readfirstlane(tok - fr);
;     const bool interior = (kb * 64 + 63 <= tb) && (MODE == 1 || kb * 64 > tb + 15 - 512);
.LBB0_231:
	s_cmp_eq_u64 s[22:23], 0
	s_ff1_i32_b64 s24, s[22:23]
	s_cselect_b32 s15, s15, s24
	s_cmp_gt_i32 s39, 0
	s_cselect_b32 s24, -1, 2
	s_add_i32 s24, s24, s39
	s_lshl_b32 s24, s24, 15
	s_add_i32 s24, s24, 0
	s_lshl_b32 s92, s15, 6
	v_lshl_add_u64 v[2:3], s[92:93], 0, v[150:151]
	v_add_u32_e32 v4, s24, v145
	v_lshlrev_b64 v[2:3], 8, v[2:3]
	v_readfirstlane_b32 s25, v4
	v_add_u32_e32 v4, 0x4000, v4
	s_waitcnt vmcnt(4)
	s_barrier
	v_lshl_add_u64 v[0:1], s[92:93], 1, v[158:159]
	v_lshl_add_u64 v[2:3], v[160:161], 0, v[2:3]
	s_mov_b32 m0, s25
	v_readfirstlane_b32 s25, v4
	global_load_lds_dwordx4 v[2:3], off
	v_lshl_add_u64 v[2:3], v[0:1], 0, v[152:153]
	s_mov_b32 m0, s25
	v_add_u32_e32 v4, s24, v149
	global_load_lds_dwordx4 v[2:3], off
	v_lshl_add_u64 v[2:3], s[92:93], 0, v[154:155]
	v_lshlrev_b64 v[2:3], 8, v[2:3]
	v_readfirstlane_b32 s24, v4
	v_lshl_add_u64 v[2:3], v[162:163], 0, v[2:3]
	s_mov_b32 m0, s24
	v_lshl_add_u64 v[0:1], v[0:1], 0, v[156:157]
	global_load_lds_dwordx4 v[2:3], off
	v_add_u32_e32 v2, 0x4000, v4
	v_mov_b32_e32 v17, v224
	v_readfirstlane_b32 s24, v2
	s_mov_b32 m0, s24
	s_lshl_b32 s24, s39, 15
	global_load_lds_dwordx4 v[0:1], off
	s_add_i32 s24, s24, 0
	v_and_b32_e32 v30, 15, v17
	v_lshrrev_b32_e32 v31, 4, v17
	v_bfe_u32 v16, v17, 4, 2
	v_bitop3_b32 v0, v31, v30, 3 bitop3:0x6c
	v_bitop3_b32 v1, v16, v30, 4 bitop3:0x36
	v_bitop3_b32 v9, v16, v30, 8 bitop3:0x36
	v_bitop3_b32 v10, v16, v30, 12 bitop3:0x36
	v_or_b32_e32 v120, 16, v30
	v_or_b32_e32 v121, 32, v30
	v_or_b32_e32 v122, 48, v30
	v_lshl_add_u32 v8, v30, 8, s24
	v_lshlrev_b32_e32 v100, 4, v0
	v_lshlrev_b32_e32 v101, 4, v1
	v_lshlrev_b32_e32 v108, 4, v9
	v_lshlrev_b32_e32 v109, 4, v10
	v_lshl_add_u32 v26, v120, 8, s24
	v_lshl_add_u32 v92, v121, 8, s24
	v_lshl_add_u32 v110, v122, 8, s24
	v_add_u32_e32 v0, v8, v100
	v_add_u32_e32 v4, v8, v101
	v_add_u32_e32 v9, v8, v108
	v_add_u32_e32 v12, v8, v109
	v_add_u32_e32 v18, v26, v100
	v_add_u32_e32 v22, v26, v101
	v_add_u32_e32 v27, v26, v108
	v_add_u32_e32 v80, v26, v109
	v_add_u32_e32 v84, v92, v100
	v_add_u32_e32 v88, v92, v101
	v_add_u32_e32 v93, v92, v108
	v_add_u32_e32 v96, v92, v109
	v_add_u32_e32 v100, v110, v100
	v_add_u32_e32 v104, v110, v101
	v_add_u32_e32 v108, v110, v108
	ds_read_b128 v[0:3], v0
	ds_read_b128 v[4:7], v4
	ds_read_b128 v[8:11], v9
	ds_read_b128 v[12:15], v12
	ds_read_b128 v[18:21], v18
	ds_read_b128 v[22:25], v22
	ds_read_b128 v[26:29], v27
	ds_read_b128 v[80:83], v80
	ds_read_b128 v[84:87], v84
	ds_read_b128 v[88:91], v88
	ds_read_b128 v[92:95], v93
	ds_read_b128 v[96:99], v96
	ds_read_b128 v[100:103], v100
	ds_read_b128 v[104:107], v104
	v_add_u32_e32 v112, v110, v109
	ds_read_b128 v[108:111], v108
	ds_read_b128 v[116:119], v112
	s_mov_b32 s25, s93
	s_mov_b32 s26, s93
	v_mov_b32_e32 v112, s25
	v_mov_b32_e32 v113, s25
	v_mov_b32_e32 v114, s25
	v_mov_b32_e32 v115, s25
	s_mov_b32 s25, s93
	v_bfe_u32 v17, v17, 1, 3
	s_waitcnt lgkmcnt(12)
	v_mfma_f32_16x16x32_bf16 v[0:3], v[0:3], v[64:67], v[112:115]
	v_mfma_f32_16x16x32_bf16 v[0:3], v[4:7], v[68:71], v[0:3]
	v_mov_b32_e32 v4, s25
	v_mov_b32_e32 v5, s25
	v_mov_b32_e32 v6, s25
	v_mfma_f32_16x16x32_bf16 v[0:3], v[8:11], v[72:75], v[0:3]
	v_mov_b32_e32 v7, s25
	v_mov_b32_e32 v8, s26
	v_mov_b32_e32 v9, s26
	v_mov_b32_e32 v10, s26
	v_mov_b32_e32 v11, s26
	s_mov_b32 s25, s93
	v_mfma_f32_16x16x32_bf16 v[0:3], v[12:15], v[76:79], v[0:3]
	s_nop 0
	v_mov_b32_e32 v12, s25
	v_mov_b32_e32 v13, s25
	v_mov_b32_e32 v14, s25
	v_mov_b32_e32 v15, s25
	s_waitcnt lgkmcnt(0)
	v_mfma_f32_16x16x32_bf16 v[8:11], v[84:87], v[64:67], v[8:11]
	s_nop 1
	v_mov_b32_e32 v173, v3
	v_mov_b32_e32 v172, v2
	v_mov_b32_e32 v170, v1
	v_mfma_f32_16x16x32_bf16 v[4:7], v[18:21], v[64:67], v[4:7]
	v_bitop3_b32 v19, v31, v17, 3 bitop3:0x6c
	v_lshl_add_u32 v18, v30, 7, s24
	v_lshlrev_b32_e32 v19, 4, v19
	v_mfma_f32_16x16x32_bf16 v[12:15], v[100:103], v[64:67], v[12:15]
	v_lshl_add_u32 v21, v120, 7, s24
	v_bitop3_b32 v17, v16, v17, 4 bitop3:0x36
	v_add_u32_e32 v20, v18, v19
	v_mfma_f32_16x16x32_bf16 v[8:11], v[88:91], v[68:71], v[8:11]
	v_lshlrev_b32_e32 v17, 4, v17
	v_add_u32_e32 v18, v18, v17
	v_mov_b32_e32 v171, v0
	v_mfma_f32_16x16x32_bf16 v[4:7], v[22:25], v[68:71], v[4:7]
	v_lshl_add_u32 v23, v121, 7, s24
	v_add_u32_e32 v22, v21, v19
	v_add_u32_e32 v24, v23, v19
	v_mfma_f32_16x16x32_bf16 v[12:15], v[104:107], v[68:71], v[12:15]
	v_lshl_add_u32 v25, v122, 7, s24
	v_add_u32_e32 v19, v25, v19
	ds_read_b128 v[132:135], v24 offset:16384
	ds_read_b128 v[128:131], v19 offset:16384
	v_mfma_f32_16x16x32_bf16 v[8:11], v[92:95], v[72:75], v[8:11]
	ds_read_b128 v[140:143], v20 offset:16384
	ds_read_b128 v[124:127], v20 offset:24576
	ds_read_b128 v[120:123], v20 offset:26624
	ds_read_b128 v[112:115], v20 offset:28672
	v_add_u32_e32 v19, v21, v17
	s_ff1_i32_b64 s24, s[20:21]
	v_mfma_f32_16x16x32_bf16 v[4:7], v[26:29], v[72:75], v[4:7]
	s_lshl_b32 s40, s24, 6
	s_or_b32 s24, s40, 63
	v_mfma_f32_16x16x32_bf16 v[12:15], v[108:111], v[72:75], v[12:15]
	v_mfma_f32_16x16x32_bf16 v[8:11], v[96:99], v[76:79], v[8:11]
	ds_read_b128 v[136:139], v22 offset:16384
	ds_read_b128 v[96:99], v20 offset:30720
	v_add_u32_e32 v20, v23, v17
	v_add_u32_e32 v17, v25, v17
	v_mfma_f32_16x16x32_bf16 v[4:7], v[80:83], v[76:79], v[4:7]
	s_nop 2
	v_mov_b32_e32 v181, v11
	v_mov_b32_e32 v180, v10
	v_mov_b32_e32 v178, v9
	v_mfma_f32_16x16x32_bf16 v[12:15], v[116:119], v[76:79], v[12:15]
	ds_read_b128 v[100:103], v20 offset:16384
	ds_read_b128 v[104:107], v17 offset:16384
	ds_read_b128 v[108:111], v18 offset:16384
	ds_read_b128 v[92:95], v18 offset:24576
	ds_read_b128 v[80:83], v18 offset:26624
	ds_read_b128 v[84:87], v18 offset:28672
	ds_read_b128 v[116:119], v19 offset:16384
	ds_read_b128 v[88:91], v18 offset:30720
	v_sub_u32_e32 v17, v164, v30
	v_mov_b32_e32 v179, v8
	v_readfirstlane_b32 s26, v17
	s_cmp_gt_i32 s24, s26
	s_cselect_b64 s[24:25], -1, 0
	s_addk_i32 s26, 0xfe0f
	s_cmp_le_i32 s40, s26
	s_cselect_b64 s[26:27], -1, 0
	s_or_b64 s[24:25], s[24:25], s[26:27]
	s_mov_b64 s[26:27], -1
	s_and_b64 vcc, exec, s[24:25]
	v_mov_b32_e32 v185, v15
	v_mov_b32_e32 v184, v14
	v_mov_b32_e32 v183, v13
	v_mov_b32_e32 v182, v12
	v_mov_b32_e32 v177, v7
	v_mov_b32_e32 v176, v6
	v_mov_b32_e32 v175, v5
	v_mov_b32_e32 v174, v4
	s_cbranch_vccz .LBB0_233
; template <int MODE>
; __device__ __forceinline__ void attn_compute(const bf16x8 (&qf)[4], const unsigned char* Ks, const unsigned char* Vs, int kb, int tok,
;                                              unsigned long long msk, f32x4 (&O)[8], float& mrow, float& lrow) {
;     ...
;     } else {
; #pragma unroll
;         for (int nt = 0; nt < 4; ++nt)
; #pragma unroll
;             for (int c = 0; c < 4; ++c) {
;                 const int key = key0 + 32 * (nt >> 1) + 4 * (nt & 1) + c;
;                 const bool ok = rowok && (key <= tok) && (MODE == 1 || key > tok - 512);
;                 S[nt][c] = ok ? S[nt][c] : -1e30f;
;                 mx = fmaxf(mx, S[nt][c]);
;             }
;     }
	v_lshl_or_b32 v16, v16, 3, s40
	v_cmp_le_i32_e32 vcc, v16, v164
	v_cmp_gt_i32_e64 s[40:41], v16, v165
	s_and_b64 vcc, vcc, s[40:41]
	v_cndmask_b32_e32 v171, v229, v0, vcc
	v_cmp_lt_i32_e32 vcc, v16, v164
	v_cmp_ge_i32_e64 s[40:41], v16, v165
	s_and_b64 vcc, vcc, s[40:41]
	v_or_b32_e32 v18, 2, v16
	v_cndmask_b32_e32 v170, v229, v1, vcc
	v_cmp_le_i32_e32 vcc, v18, v164
	v_cmp_gt_i32_e64 s[40:41], v18, v165
	s_and_b64 vcc, vcc, s[40:41]
	v_or_b32_e32 v18, 3, v16
	v_cndmask_b32_e32 v172, v229, v2, vcc
	v_cmp_le_i32_e32 vcc, v18, v164
	v_cmp_gt_i32_e64 s[40:41], v18, v165
	s_and_b64 vcc, vcc, s[40:41]
	v_or_b32_e32 v18, 4, v16
	v_cndmask_b32_e32 v173, v229, v3, vcc
	v_cmp_le_i32_e32 vcc, v18, v164
	v_cmp_gt_i32_e64 s[40:41], v18, v165
	s_and_b64 vcc, vcc, s[40:41]
	v_or_b32_e32 v18, 5, v16
	v_cndmask_b32_e32 v174, v229, v4, vcc
	v_cmp_le_i32_e32 vcc, v18, v164
	v_cmp_gt_i32_e64 s[40:41], v18, v165
	s_and_b64 vcc, vcc, s[40:41]
	v_or_b32_e32 v18, 6, v16
	v_cndmask_b32_e32 v175, v229, v5, vcc
	v_cmp_le_i32_e32 vcc, v18, v164
	v_cmp_gt_i32_e64 s[40:41], v18, v165
	s_and_b64 vcc, vcc, s[40:41]
	v_or_b32_e32 v18, 7, v16
	v_cndmask_b32_e32 v176, v229, v6, vcc
	v_cmp_le_i32_e32 vcc, v18, v164
	v_cmp_gt_i32_e64 s[40:41], v18, v165
	s_and_b64 vcc, vcc, s[40:41]
	v_or_b32_e32 v18, 32, v16
	v_cndmask_b32_e32 v177, v229, v7, vcc
	v_cmp_le_i32_e32 vcc, v18, v164
	v_cmp_gt_i32_e64 s[40:41], v18, v165
	s_and_b64 vcc, vcc, s[40:41]
	v_cndmask_b32_e32 v179, v229, v8, vcc
	v_cmp_lt_i32_e32 vcc, v18, v164
	v_cmp_ge_i32_e64 s[40:41], v18, v165
	s_and_b64 vcc, vcc, s[40:41]
	v_or_b32_e32 v18, 34, v16
	v_cndmask_b32_e32 v178, v229, v9, vcc
	v_cmp_le_i32_e32 vcc, v18, v164
	v_cmp_gt_i32_e64 s[40:41], v18, v165
	s_and_b64 vcc, vcc, s[40:41]
	v_or_b32_e32 v18, 35, v16
	v_cndmask_b32_e32 v180, v229, v10, vcc
	v_cmp_le_i32_e32 vcc, v18, v164
	v_cmp_gt_i32_e64 s[40:41], v18, v165
	s_and_b64 vcc, vcc, s[40:41]
	v_or_b32_e32 v18, 36, v16
	v_cndmask_b32_e32 v181, v229, v11, vcc
	v_cmp_le_i32_e32 vcc, v18, v164
	v_cmp_gt_i32_e64 s[40:41], v18, v165
	s_mov_b32 s26, 0xf149f2ca
	s_and_b64 vcc, vcc, s[40:41]
	v_or_b32_e32 v18, 37, v16
	v_max3_f32 v17, v171, s26, v170
	v_cndmask_b32_e32 v182, v229, v12, vcc
	v_cmp_le_i32_e32 vcc, v18, v164
	v_cmp_gt_i32_e64 s[40:41], v18, v165
	v_max3_f32 v17, v17, v172, v173
	s_and_b64 vcc, vcc, s[40:41]
	v_or_b32_e32 v18, 38, v16
	v_max3_f32 v17, v17, v174, v175
	v_cndmask_b32_e32 v183, v229, v13, vcc
	v_cmp_le_i32_e32 vcc, v18, v164
	v_cmp_gt_i32_e64 s[40:41], v18, v165
	v_max3_f32 v17, v17, v176, v177
	s_and_b64 vcc, vcc, s[40:41]
	v_or_b32_e32 v16, 39, v16
	v_max3_f32 v17, v17, v179, v178
	v_cndmask_b32_e32 v184, v229, v14, vcc
	v_cmp_le_i32_e32 vcc, v16, v164
	v_cmp_gt_i32_e64 s[40:41], v16, v165
	v_max3_f32 v17, v17, v180, v181
	s_and_b64 vcc, vcc, s[40:41]
	v_max3_f32 v17, v17, v182, v183
	v_cndmask_b32_e32 v185, v229, v15, vcc
	v_max3_f32 v17, v17, v184, v185
	s_mov_b64 s[26:27], 0
